# grid barriers: the L1 invalidate of the acquire is issued right after the workgroup's arrive atomic (a CU reads none of the next phase's inputs between its arrive and the release), so it no longer fol
# speedup vs baseline: 1.0184x; 1.0080x over previous
; __device__ __forceinline__ unsigned xb_add(unsigned* p, unsigned v) { return __hip_atomic_fetch_add(p, v, __ATOMIC_RELAXED, __HIP_MEMORY_SCOPE_AGENT); }
; __device__ __forceinline__ void xcd_barrier(const XcdBarrier& b) {
;     ...
;     if (threadIdx.x == 0) {
;         unsigned* bar = b.bar;
;         __builtin_amdgcn_s_waitcnt(0);
;         unsigned nloc = b.st[0], nx = b.st[1];
;         if (nloc == 0u) { xcd_barrier_complete(bar, b.x, nloc, nx); b.st[0] = nloc; b.st[1] = nx; }
;         const unsigned old = xb_add(&bar[XB_XSUB(b.x)], 1u);
;         const unsigned gen = old / nloc;
;         if (old + 1u == (gen + 1u) * nloc) {
.LBB0_149:
	s_mov_b64 s[4:5], exec
	v_mbcnt_lo_u32_b32 v1, s4, 0
	v_mbcnt_hi_u32_b32 v1, s5, v1
	v_cmp_eq_u32_e32 vcc, 0, v1
	s_and_saveexec_b64 s[2:3], vcc
	s_cbranch_execz .LBB0_151
	s_lshl_b32 s6, s36, 8
	s_add_u32 s6, s20, s6
	s_addc_u32 s7, s21, 0
	s_bcnt1_i32_b64 s4, s[4:5]
	v_mov_b32_e32 v3, 0x1000
	v_mov_b32_e32 v4, s4
	global_atomic_add v3, v3, v4, s[6:7] offset:1024 sc0
	buffer_inv sc1

; __device__ __forceinline__ unsigned xb_ld(unsigned* p)              { return __hip_atomic_load(p, __ATOMIC_RELAXED, __HIP_MEMORY_SCOPE_AGENT); }
; __device__ __forceinline__ unsigned xb_add(unsigned* p, unsigned v) { return __hip_atomic_fetch_add(p, v, __ATOMIC_RELAXED, __HIP_MEMORY_SCOPE_AGENT); }
; #define XB_SPIN(cond, bar) do { unsigned _sp = 0; while (cond) { __builtin_amdgcn_s_sleep(1); \
;     if ((++_sp & 255u) == 0u) { if (xb_ld(&(bar)[XB_TMO])) break; if (_sp > XB_SPIN_CAP) { atomicAdd(&(bar)[XB_TMO], 1u); break; } } } } while (0)
; __device__ __forceinline__ void xcd_barrier(const XcdBarrier& b) {
;     ...
;             const unsigned tg = og / nx;
;             if (og + 1u == (tg + 1u) * nx) xb_add(&bar[XB_TOPGEN], 1u);
;             else XB_SPIN(xb_ld(&bar[XB_TOPGEN]) == tg, bar);
;             __builtin_amdgcn_fence(__ATOMIC_ACQUIRE, "agent");
;             xb_add(&bar[XB_XGEN(b.x)], 1u);
;             asm volatile("s_waitcnt vmcnt(0)" ::: "memory");
.LBB0_230:
	s_mov_b64 s[4:5], exec
	v_mbcnt_lo_u32_b32 v1, s4, 0
	v_mbcnt_hi_u32_b32 v1, s5, v1
	v_cmp_eq_u32_e32 vcc, 0, v1
	s_waitcnt vmcnt(0)
	s_and_saveexec_b64 s[2:3], vcc
	s_cbranch_execz .LBB0_232
	s_lshl_b32 s6, s36, 8
	s_add_u32 s6, s20, s6
	s_addc_u32 s7, s21, 0
	s_bcnt1_i32_b64 s4, s[4:5]
	v_mov_b32_e32 v1, 0x2000
	v_mov_b32_e32 v2, s4
	global_atomic_add v1, v2, s[6:7] offset:1024

; __device__ __forceinline__ unsigned xb_ld(unsigned* p)              { return __hip_atomic_load(p, __ATOMIC_RELAXED, __HIP_MEMORY_SCOPE_AGENT); }
; #define XB_SPIN(cond, bar) do { unsigned _sp = 0; while (cond) { __builtin_amdgcn_s_sleep(1); \
;     if ((++_sp & 255u) == 0u) { if (xb_ld(&(bar)[XB_TMO])) break; if (_sp > XB_SPIN_CAP) { atomicAdd(&(bar)[XB_TMO], 1u); break; } } } } while (0)
; __device__ __forceinline__ void xcd_barrier(const XcdBarrier& b) {
;     ...
;         } else {
;             XB_SPIN(xb_ld(&bar[XB_TOPGEN]) == gen, bar);
;             __builtin_amdgcn_fence(__ATOMIC_ACQUIRE, "agent");
;             asm volatile("s_waitcnt vmcnt(0)" ::: "memory");
.LBB0_246:
	s_waitcnt vmcnt(0)
	s_waitcnt vmcnt(0)

; __device__ __forceinline__ unsigned xb_add(unsigned* p, unsigned v) { return __hip_atomic_fetch_add(p, v, __ATOMIC_RELAXED, __HIP_MEMORY_SCOPE_AGENT); }
; __device__ __forceinline__ void xcd_barrier(const XcdBarrier& b) {
;     ...
;         const unsigned old = xb_add(&bar[XB_XSUB(b.x)], 1u);
;         const unsigned gen = old / nloc;
;         if (old + 1u == (gen + 1u) * nloc) {
.LBB0_362:
	s_mov_b64 s[4:5], exec
	v_mbcnt_lo_u32_b32 v1, s4, 0
	v_mbcnt_hi_u32_b32 v1, s5, v1
	v_cmp_eq_u32_e32 vcc, 0, v1
	s_and_saveexec_b64 s[2:3], vcc
	s_cbranch_execz .LBB0_364
	s_bcnt1_i32_b64 s4, s[4:5]
	v_mov_b32_e32 v3, s4
	v_readlane_b32 s4, v254, 25
	v_readlane_b32 s5, v254, 26
	s_nop 4
	global_atomic_add v3, v169, v3, s[4:5] sc0
	buffer_inv sc1

; __device__ __forceinline__ unsigned xb_ld(unsigned* p)              { return __hip_atomic_load(p, __ATOMIC_RELAXED, __HIP_MEMORY_SCOPE_AGENT); }
; #define XB_SPIN(cond, bar) do { unsigned _sp = 0; while (cond) { __builtin_amdgcn_s_sleep(1); \
;     if ((++_sp & 255u) == 0u) { if (xb_ld(&(bar)[XB_TMO])) break; if (_sp > XB_SPIN_CAP) { atomicAdd(&(bar)[XB_TMO], 1u); break; } } } } while (0)
; __device__ __forceinline__ void xcd_barrier(const XcdBarrier& b) {
;     ...
;         } else {
;             XB_SPIN(xb_ld(&bar[XB_TOPGEN]) == gen, bar);
;             __builtin_amdgcn_fence(__ATOMIC_ACQUIRE, "agent");
;             asm volatile("s_waitcnt vmcnt(0)" ::: "memory");
.LBB0_377:
	s_or_b64 exec, exec, s[4:5]
	s_waitcnt vmcnt(0)
	s_waitcnt vmcnt(0)

; __device__ __forceinline__ unsigned xb_ld(unsigned* p)              { return __hip_atomic_load(p, __ATOMIC_RELAXED, __HIP_MEMORY_SCOPE_AGENT); }
; __device__ __forceinline__ unsigned xb_add(unsigned* p, unsigned v) { return __hip_atomic_fetch_add(p, v, __ATOMIC_RELAXED, __HIP_MEMORY_SCOPE_AGENT); }
; #define XB_SPIN(cond, bar) do { unsigned _sp = 0; while (cond) { __builtin_amdgcn_s_sleep(1); \
;     if ((++_sp & 255u) == 0u) { if (xb_ld(&(bar)[XB_TMO])) break; if (_sp > XB_SPIN_CAP) { atomicAdd(&(bar)[XB_TMO], 1u); break; } } } } while (0)
; __device__ __forceinline__ void xcd_barrier(const XcdBarrier& b) {
;     ...
;             else XB_SPIN(xb_ld(&bar[XB_TOPGEN]) == tg, bar);
;             __builtin_amdgcn_fence(__ATOMIC_ACQUIRE, "agent");
;             xb_add(&bar[XB_XGEN(b.x)], 1u);
;             asm volatile("s_waitcnt vmcnt(0)" ::: "memory");
.LBB0_395:
	s_or_b64 exec, exec, s[2:3]
	s_mov_b64 s[2:3], exec
	v_mbcnt_lo_u32_b32 v0, s2, 0
	v_mbcnt_hi_u32_b32 v0, s3, v0
	v_cmp_eq_u32_e32 vcc, 0, v0
	s_waitcnt vmcnt(0)
	s_and_saveexec_b64 s[4:5], vcc
	s_cbranch_execz .LBB0_397
	s_bcnt1_i32_b64 s2, s[2:3]
	v_mov_b32_e32 v0, s2
	v_readlane_b32 s2, v254, 31
	v_readlane_b32 s3, v254, 32
	s_nop 4
	global_atomic_add v169, v0, s[2:3]

; __device__ __forceinline__ unsigned xb_ld(unsigned* p)              { return __hip_atomic_load(p, __ATOMIC_RELAXED, __HIP_MEMORY_SCOPE_AGENT); }
; __device__ __forceinline__ unsigned xb_add(unsigned* p, unsigned v) { return __hip_atomic_fetch_add(p, v, __ATOMIC_RELAXED, __HIP_MEMORY_SCOPE_AGENT); }
; #define XB_SPIN(cond, bar) do { unsigned _sp = 0; while (cond) { __builtin_amdgcn_s_sleep(1); \
;     if ((++_sp & 255u) == 0u) { if (xb_ld(&(bar)[XB_TMO])) break; if (_sp > XB_SPIN_CAP) { atomicAdd(&(bar)[XB_TMO], 1u); break; } } } } while (0)
; __device__ __forceinline__ void xcd_barrier_wait(const XcdBarrier& b) {
;     ...
;             if (role == 1u) XB_SPIN(xb_ld(&bar[XB_TOPGEN]) == tg, bar);
;             __builtin_amdgcn_fence(__ATOMIC_ACQUIRE, "agent");
;             xb_add(&bar[XB_XGEN(b.x)], 1u);
;             asm volatile("s_waitcnt vmcnt(0)" ::: "memory");
.LBB0_497:
	s_mov_b64 s[2:3], exec
	s_waitcnt lgkmcnt(0)
	v_mbcnt_lo_u32_b32 v1, s2, 0
	v_mbcnt_hi_u32_b32 v1, s3, v1
	v_cmp_eq_u32_e32 vcc, 0, v1
	s_waitcnt vmcnt(0)
	s_and_saveexec_b64 s[4:5], vcc
	s_cbranch_execz .LBB0_499
	s_bcnt1_i32_b64 s2, s[2:3]
	v_mov_b32_e32 v1, s2
	v_readlane_b32 s2, v254, 31
	v_readlane_b32 s3, v254, 32
	s_nop 4
	global_atomic_add v169, v1, s[2:3]
